# in-proj V^T path: pairs of 2-byte token stores merged into 4-byte stores (DPP neighbour exchange)
# speedup vs baseline: 1.0238x; 1.0018x over previous
; __device__ __forceinline__ unsigned cvt_pk_bf16(float lo, float hi) { unsigned r; asm volatile("v_cvt_pk_bf16_f32 %0, %1, %2" : "=v"(r) : "v"(lo), "v"(hi)); return r; }
;     __device__ __forceinline__ void operator()(f32x4 (&acc)[2][2][4][2], const Unit& u, int wr, int wc, int fr, int fq) const {
;     ...
;             bf16_t* tp = T + (size_t)(colt - t_col0) * ldt + row0;
; #pragma unroll
;             for (int bj = 0; bj < 2; ++bj) {
; #pragma unroll
;                 for (int n = 0; n < 2; ++n)
; #pragma unroll
;                     for (int j = 0; j < 4; ++j) {
; #pragma unroll
;                         for (int ai = 0; ai < 2; ++ai)
; #pragma unroll
;                             for (int m = 0; m < 4; ++m) tp[ai * HALF + m * 16] = (bf16_t)(cvt_pk_bf16(acc[ai][bj][m][n][j], 0.f) & 0xffffu);
;                         tp += ldt; asm volatile("" : "+v"(tp)); }
;                 tp += (size_t)120 * ldt; asm volatile("" : "+v"(tp)); }
.LBB0_277:
	v_lshlrev_b32_e32 v0, 17, v174
	v_lshl_add_u64 v[130:131], s[18:19], 0, v[0:1]
	v_lshl_add_u64 v[130:131], v[172:173], 1, v[130:131]
	v_and_b32_e32 v238, 1, v229
	v_mul_u32_u24_e32 v238, 30, v238
	v_mov_b32_e32 v239, 0
	v_lshl_add_u64 v[130:131], v[130:131], 0, v[238:239]
	s_mov_b32 vcc_lo, 0xaaaaaaaa
	s_mov_b32 vcc_hi, 0xaaaaaaaa
	v_mov_b32_dpp v224, v126 quad_perm:[1,0,3,2] row_mask:0xf bank_mask:0xf
	v_mov_b32_dpp v225, v122 quad_perm:[1,0,3,2] row_mask:0xf bank_mask:0xf
	v_cndmask_b32_e32 v226, v126, v225, vcc
	v_cndmask_b32_e32 v227, v224, v122, vcc
	v_cvt_pk_bf16_f32 v0, v226, v227
	global_store_dword v[130:131], v0, off
	v_mov_b32_dpp v224, v118 quad_perm:[1,0,3,2] row_mask:0xf bank_mask:0xf
	v_mov_b32_dpp v225, v114 quad_perm:[1,0,3,2] row_mask:0xf bank_mask:0xf
	v_cndmask_b32_e32 v226, v118, v225, vcc
	v_cndmask_b32_e32 v227, v224, v114, vcc
	v_cvt_pk_bf16_f32 v0, v226, v227
	global_store_dword v[130:131], v0, off offset:64
	v_mov_b32_dpp v224, v110 quad_perm:[1,0,3,2] row_mask:0xf bank_mask:0xf
	v_mov_b32_dpp v225, v106 quad_perm:[1,0,3,2] row_mask:0xf bank_mask:0xf
	v_cndmask_b32_e32 v226, v110, v225, vcc
	v_cndmask_b32_e32 v227, v224, v106, vcc
	v_cvt_pk_bf16_f32 v0, v226, v227
	global_store_dword v[130:131], v0, off offset:256
	s_mov_b64 s[0:1], 0x20000
	v_mov_b32_dpp v224, v102 quad_perm:[1,0,3,2] row_mask:0xf bank_mask:0xf
	v_mov_b32_dpp v225, v98 quad_perm:[1,0,3,2] row_mask:0xf bank_mask:0xf
	v_cndmask_b32_e32 v226, v102, v225, vcc
	v_cndmask_b32_e32 v227, v224, v98, vcc
	v_cvt_pk_bf16_f32 v0, v226, v227
	global_store_dword v[130:131], v0, off offset:320
	v_lshl_add_u64 v[130:131], v[130:131], 0, s[0:1]
	v_mov_b32_dpp v224, v127 quad_perm:[1,0,3,2] row_mask:0xf bank_mask:0xf
	v_mov_b32_dpp v225, v123 quad_perm:[1,0,3,2] row_mask:0xf bank_mask:0xf
	v_cndmask_b32_e32 v226, v127, v225, vcc
	v_cndmask_b32_e32 v227, v224, v123, vcc
	v_cvt_pk_bf16_f32 v0, v226, v227
	global_store_dword v[130:131], v0, off
	v_mov_b32_dpp v224, v119 quad_perm:[1,0,3,2] row_mask:0xf bank_mask:0xf
	v_mov_b32_dpp v225, v115 quad_perm:[1,0,3,2] row_mask:0xf bank_mask:0xf
	v_cndmask_b32_e32 v226, v119, v225, vcc
	v_cndmask_b32_e32 v227, v224, v115, vcc
	v_cvt_pk_bf16_f32 v0, v226, v227
	global_store_dword v[130:131], v0, off offset:64
	v_mov_b32_dpp v224, v111 quad_perm:[1,0,3,2] row_mask:0xf bank_mask:0xf
	v_mov_b32_dpp v225, v107 quad_perm:[1,0,3,2] row_mask:0xf bank_mask:0xf
	v_cndmask_b32_e32 v226, v111, v225, vcc
	v_cndmask_b32_e32 v227, v224, v107, vcc
	v_cvt_pk_bf16_f32 v0, v226, v227
	global_store_dword v[130:131], v0, off offset:256
	v_mov_b32_dpp v224, v103 quad_perm:[1,0,3,2] row_mask:0xf bank_mask:0xf
	v_mov_b32_dpp v225, v99 quad_perm:[1,0,3,2] row_mask:0xf bank_mask:0xf
	v_cndmask_b32_e32 v226, v103, v225, vcc
	v_cndmask_b32_e32 v227, v224, v99, vcc
	v_cvt_pk_bf16_f32 v0, v226, v227
	v_lshl_add_u64 v[98:99], v[130:131], 0, s[0:1]
	global_store_dword v[130:131], v0, off offset:320
	v_mov_b32_dpp v224, v128 quad_perm:[1,0,3,2] row_mask:0xf bank_mask:0xf
	v_mov_b32_dpp v225, v124 quad_perm:[1,0,3,2] row_mask:0xf bank_mask:0xf
	v_cndmask_b32_e32 v226, v128, v225, vcc
	v_cndmask_b32_e32 v227, v224, v124, vcc
	v_cvt_pk_bf16_f32 v0, v226, v227
	global_store_dword v[98:99], v0, off
	v_mov_b32_dpp v224, v120 quad_perm:[1,0,3,2] row_mask:0xf bank_mask:0xf
	v_mov_b32_dpp v225, v116 quad_perm:[1,0,3,2] row_mask:0xf bank_mask:0xf
	v_cndmask_b32_e32 v226, v120, v225, vcc
	v_cndmask_b32_e32 v227, v224, v116, vcc
	v_cvt_pk_bf16_f32 v0, v226, v227
	global_store_dword v[98:99], v0, off offset:64
	v_mov_b32_dpp v224, v112 quad_perm:[1,0,3,2] row_mask:0xf bank_mask:0xf
	v_mov_b32_dpp v225, v108 quad_perm:[1,0,3,2] row_mask:0xf bank_mask:0xf
	v_cndmask_b32_e32 v226, v112, v225, vcc
	v_cndmask_b32_e32 v227, v224, v108, vcc
	v_cvt_pk_bf16_f32 v0, v226, v227
	global_store_dword v[98:99], v0, off offset:256
	v_mov_b32_dpp v224, v104 quad_perm:[1,0,3,2] row_mask:0xf bank_mask:0xf
	v_mov_b32_dpp v225, v100 quad_perm:[1,0,3,2] row_mask:0xf bank_mask:0xf
	v_cndmask_b32_e32 v226, v104, v225, vcc
	v_cndmask_b32_e32 v227, v224, v100, vcc
	v_cvt_pk_bf16_f32 v0, v226, v227
	global_store_dword v[98:99], v0, off offset:320
	v_lshl_add_u64 v[98:99], v[98:99], 0, s[0:1]
	v_mov_b32_dpp v224, v129 quad_perm:[1,0,3,2] row_mask:0xf bank_mask:0xf
	v_mov_b32_dpp v225, v125 quad_perm:[1,0,3,2] row_mask:0xf bank_mask:0xf
	v_cndmask_b32_e32 v226, v129, v225, vcc
	v_cndmask_b32_e32 v227, v224, v125, vcc
	v_cvt_pk_bf16_f32 v0, v226, v227
	global_store_dword v[98:99], v0, off
	v_mov_b32_dpp v224, v121 quad_perm:[1,0,3,2] row_mask:0xf bank_mask:0xf
	v_mov_b32_dpp v225, v117 quad_perm:[1,0,3,2] row_mask:0xf bank_mask:0xf
	v_cndmask_b32_e32 v226, v121, v225, vcc
	v_cndmask_b32_e32 v227, v224, v117, vcc
	v_cvt_pk_bf16_f32 v0, v226, v227
	global_store_dword v[98:99], v0, off offset:64
	v_mov_b32_dpp v224, v113 quad_perm:[1,0,3,2] row_mask:0xf bank_mask:0xf
	v_mov_b32_dpp v225, v109 quad_perm:[1,0,3,2] row_mask:0xf bank_mask:0xf
	v_cndmask_b32_e32 v226, v113, v225, vcc
	v_cndmask_b32_e32 v227, v224, v109, vcc
	v_cvt_pk_bf16_f32 v0, v226, v227
	global_store_dword v[98:99], v0, off offset:256
	v_mov_b32_dpp v224, v105 quad_perm:[1,0,3,2] row_mask:0xf bank_mask:0xf
	v_mov_b32_dpp v225, v101 quad_perm:[1,0,3,2] row_mask:0xf bank_mask:0xf
	v_cndmask_b32_e32 v226, v105, v225, vcc
	v_cndmask_b32_e32 v227, v224, v101, vcc
	v_cvt_pk_bf16_f32 v0, v226, v227
	global_store_dword v[98:99], v0, off offset:320
	v_lshl_add_u64 v[98:99], v[98:99], 0, s[0:1]
	v_mov_b32_dpp v224, v94 quad_perm:[1,0,3,2] row_mask:0xf bank_mask:0xf
	v_mov_b32_dpp v225, v90 quad_perm:[1,0,3,2] row_mask:0xf bank_mask:0xf
; __device__ __forceinline__ unsigned cvt_pk_bf16(float lo, float hi) { unsigned r; asm volatile("v_cvt_pk_bf16_f32 %0, %1, %2" : "=v"(r) : "v"(lo), "v"(hi)); return r; }
;     __device__ __forceinline__ void operator()(f32x4 (&acc)[2][2][4][2], const Unit& u, int wr, int wc, int fr, int fq) const {
;     ...
;             bf16_t* tp = T + (size_t)(colt - t_col0) * ldt + row0;
; #pragma unroll
;             for (int bj = 0; bj < 2; ++bj) {
; #pragma unroll
;                 for (int n = 0; n < 2; ++n)
; #pragma unroll
;                     for (int j = 0; j < 4; ++j) {
; #pragma unroll
;                         for (int ai = 0; ai < 2; ++ai)
; #pragma unroll
;                             for (int m = 0; m < 4; ++m) tp[ai * HALF + m * 16] = (bf16_t)(cvt_pk_bf16(acc[ai][bj][m][n][j], 0.f) & 0xffffu);
;                         tp += ldt; asm volatile("" : "+v"(tp)); }
;                 tp += (size_t)120 * ldt; asm volatile("" : "+v"(tp)); }
	v_cndmask_b32_e32 v226, v94, v225, vcc
	v_cndmask_b32_e32 v227, v224, v90, vcc
	v_cvt_pk_bf16_f32 v0, v226, v227
	global_store_dword v[98:99], v0, off
	v_mov_b32_dpp v224, v86 quad_perm:[1,0,3,2] row_mask:0xf bank_mask:0xf
	v_mov_b32_dpp v225, v82 quad_perm:[1,0,3,2] row_mask:0xf bank_mask:0xf
	v_cndmask_b32_e32 v226, v86, v225, vcc
	v_cndmask_b32_e32 v227, v224, v82, vcc
	v_cvt_pk_bf16_f32 v0, v226, v227
	global_store_dword v[98:99], v0, off offset:64
	v_mov_b32_dpp v224, v78 quad_perm:[1,0,3,2] row_mask:0xf bank_mask:0xf
	v_mov_b32_dpp v225, v74 quad_perm:[1,0,3,2] row_mask:0xf bank_mask:0xf
	v_cndmask_b32_e32 v226, v78, v225, vcc
	v_cndmask_b32_e32 v227, v224, v74, vcc
	v_cvt_pk_bf16_f32 v0, v226, v227
	global_store_dword v[98:99], v0, off offset:256
	v_mov_b32_dpp v224, v70 quad_perm:[1,0,3,2] row_mask:0xf bank_mask:0xf
	v_mov_b32_dpp v225, v66 quad_perm:[1,0,3,2] row_mask:0xf bank_mask:0xf
	v_cndmask_b32_e32 v226, v70, v225, vcc
	v_cndmask_b32_e32 v227, v224, v66, vcc
	v_cvt_pk_bf16_f32 v0, v226, v227
	global_store_dword v[98:99], v0, off offset:320
	v_lshl_add_u64 v[98:99], v[98:99], 0, s[0:1]
	v_mov_b32_dpp v224, v95 quad_perm:[1,0,3,2] row_mask:0xf bank_mask:0xf
	v_mov_b32_dpp v225, v91 quad_perm:[1,0,3,2] row_mask:0xf bank_mask:0xf
	v_cndmask_b32_e32 v226, v95, v225, vcc
	v_cndmask_b32_e32 v227, v224, v91, vcc
	v_cvt_pk_bf16_f32 v0, v226, v227
	global_store_dword v[98:99], v0, off
	v_mov_b32_dpp v224, v87 quad_perm:[1,0,3,2] row_mask:0xf bank_mask:0xf
	v_mov_b32_dpp v225, v83 quad_perm:[1,0,3,2] row_mask:0xf bank_mask:0xf
	v_cndmask_b32_e32 v226, v87, v225, vcc
	v_cndmask_b32_e32 v227, v224, v83, vcc
	v_cvt_pk_bf16_f32 v0, v226, v227
	global_store_dword v[98:99], v0, off offset:64
	v_mov_b32_dpp v224, v79 quad_perm:[1,0,3,2] row_mask:0xf bank_mask:0xf
	v_mov_b32_dpp v225, v75 quad_perm:[1,0,3,2] row_mask:0xf bank_mask:0xf
	v_cndmask_b32_e32 v226, v79, v225, vcc
	v_cndmask_b32_e32 v227, v224, v75, vcc
	v_cvt_pk_bf16_f32 v0, v226, v227
	global_store_dword v[98:99], v0, off offset:256
	v_mov_b32_dpp v224, v71 quad_perm:[1,0,3,2] row_mask:0xf bank_mask:0xf
	v_mov_b32_dpp v225, v67 quad_perm:[1,0,3,2] row_mask:0xf bank_mask:0xf
	v_cndmask_b32_e32 v226, v71, v225, vcc
	v_cndmask_b32_e32 v227, v224, v67, vcc
	v_cvt_pk_bf16_f32 v0, v226, v227
	v_lshl_add_u64 v[66:67], v[98:99], 0, s[0:1]
	global_store_dword v[98:99], v0, off offset:320
	v_mov_b32_dpp v224, v96 quad_perm:[1,0,3,2] row_mask:0xf bank_mask:0xf
	v_mov_b32_dpp v225, v92 quad_perm:[1,0,3,2] row_mask:0xf bank_mask:0xf
	v_cndmask_b32_e32 v226, v96, v225, vcc
	v_cndmask_b32_e32 v227, v224, v92, vcc
	v_cvt_pk_bf16_f32 v0, v226, v227
	global_store_dword v[66:67], v0, off
	v_mov_b32_dpp v224, v88 quad_perm:[1,0,3,2] row_mask:0xf bank_mask:0xf
	v_mov_b32_dpp v225, v84 quad_perm:[1,0,3,2] row_mask:0xf bank_mask:0xf
	v_cndmask_b32_e32 v226, v88, v225, vcc
	v_cndmask_b32_e32 v227, v224, v84, vcc
	v_cvt_pk_bf16_f32 v0, v226, v227
	global_store_dword v[66:67], v0, off offset:64
	v_mov_b32_dpp v224, v80 quad_perm:[1,0,3,2] row_mask:0xf bank_mask:0xf
	v_mov_b32_dpp v225, v76 quad_perm:[1,0,3,2] row_mask:0xf bank_mask:0xf
	v_cndmask_b32_e32 v226, v80, v225, vcc
	v_cndmask_b32_e32 v227, v224, v76, vcc
	v_cvt_pk_bf16_f32 v0, v226, v227
	global_store_dword v[66:67], v0, off offset:256
	v_mov_b32_dpp v224, v72 quad_perm:[1,0,3,2] row_mask:0xf bank_mask:0xf
	v_mov_b32_dpp v225, v68 quad_perm:[1,0,3,2] row_mask:0xf bank_mask:0xf
	v_cndmask_b32_e32 v226, v72, v225, vcc
	v_cndmask_b32_e32 v227, v224, v68, vcc
	v_cvt_pk_bf16_f32 v0, v226, v227
	global_store_dword v[66:67], v0, off offset:320
	v_lshl_add_u64 v[66:67], v[66:67], 0, s[0:1]
	v_mov_b32_dpp v224, v97 quad_perm:[1,0,3,2] row_mask:0xf bank_mask:0xf
	v_mov_b32_dpp v225, v93 quad_perm:[1,0,3,2] row_mask:0xf bank_mask:0xf
	v_cndmask_b32_e32 v226, v97, v225, vcc
	v_cndmask_b32_e32 v227, v224, v93, vcc
	v_cvt_pk_bf16_f32 v0, v226, v227
	global_store_dword v[66:67], v0, off
	v_mov_b32_dpp v224, v89 quad_perm:[1,0,3,2] row_mask:0xf bank_mask:0xf
	v_mov_b32_dpp v225, v85 quad_perm:[1,0,3,2] row_mask:0xf bank_mask:0xf
	v_cndmask_b32_e32 v226, v89, v225, vcc
	v_cndmask_b32_e32 v227, v224, v85, vcc
	v_cvt_pk_bf16_f32 v0, v226, v227
	global_store_dword v[66:67], v0, off offset:64
	v_mov_b32_dpp v224, v81 quad_perm:[1,0,3,2] row_mask:0xf bank_mask:0xf
	v_mov_b32_dpp v225, v77 quad_perm:[1,0,3,2] row_mask:0xf bank_mask:0xf
	v_cndmask_b32_e32 v226, v81, v225, vcc
	v_cndmask_b32_e32 v227, v224, v77, vcc
	v_cvt_pk_bf16_f32 v0, v226, v227
	global_store_dword v[66:67], v0, off offset:256
	v_mov_b32_dpp v224, v73 quad_perm:[1,0,3,2] row_mask:0xf bank_mask:0xf
	v_mov_b32_dpp v225, v69 quad_perm:[1,0,3,2] row_mask:0xf bank_mask:0xf
	v_cndmask_b32_e32 v226, v73, v225, vcc
	v_cndmask_b32_e32 v227, v224, v69, vcc
	v_cvt_pk_bf16_f32 v0, v226, v227
	global_store_dword v[66:67], v0, off offset:320
	v_lshl_add_u64 v[66:67], v[66:67], 0, s[0:1]
	s_mov_b64 s[6:7], 0xf00000
	v_lshl_add_u64 v[66:67], v[66:67], 0, s[6:7]
	v_mov_b32_dpp v224, v62 quad_perm:[1,0,3,2] row_mask:0xf bank_mask:0xf
	v_mov_b32_dpp v225, v58 quad_perm:[1,0,3,2] row_mask:0xf bank_mask:0xf
	v_cndmask_b32_e32 v226, v62, v225, vcc
	v_cndmask_b32_e32 v227, v224, v58, vcc
	v_cvt_pk_bf16_f32 v0, v226, v227
	global_store_dword v[66:67], v0, off
	v_mov_b32_dpp v224, v54 quad_perm:[1,0,3,2] row_mask:0xf bank_mask:0xf
	v_mov_b32_dpp v225, v50 quad_perm:[1,0,3,2] row_mask:0xf bank_mask:0xf
	v_cndmask_b32_e32 v226, v54, v225, vcc
	v_cndmask_b32_e32 v227, v224, v50, vcc
	v_cvt_pk_bf16_f32 v0, v226, v227
	global_store_dword v[66:67], v0, off offset:64
	v_mov_b32_dpp v224, v46 quad_perm:[1,0,3,2] row_mask:0xf bank_mask:0xf
; __device__ __forceinline__ unsigned cvt_pk_bf16(float lo, float hi) { unsigned r; asm volatile("v_cvt_pk_bf16_f32 %0, %1, %2" : "=v"(r) : "v"(lo), "v"(hi)); return r; }
;     __device__ __forceinline__ void operator()(f32x4 (&acc)[2][2][4][2], const Unit& u, int wr, int wc, int fr, int fq) const {
;     ...
;             bf16_t* tp = T + (size_t)(colt - t_col0) * ldt + row0;
; #pragma unroll
;             for (int bj = 0; bj < 2; ++bj) {
; #pragma unroll
;                 for (int n = 0; n < 2; ++n)
; #pragma unroll
;                     for (int j = 0; j < 4; ++j) {
; #pragma unroll
;                         for (int ai = 0; ai < 2; ++ai)
; #pragma unroll
;                             for (int m = 0; m < 4; ++m) tp[ai * HALF + m * 16] = (bf16_t)(cvt_pk_bf16(acc[ai][bj][m][n][j], 0.f) & 0xffffu);
;                         tp += ldt; asm volatile("" : "+v"(tp)); }
;                 tp += (size_t)120 * ldt; asm volatile("" : "+v"(tp)); }
	v_mov_b32_dpp v225, v42 quad_perm:[1,0,3,2] row_mask:0xf bank_mask:0xf
	v_cndmask_b32_e32 v226, v46, v225, vcc
	v_cndmask_b32_e32 v227, v224, v42, vcc
	v_cvt_pk_bf16_f32 v0, v226, v227
	global_store_dword v[66:67], v0, off offset:256
	v_mov_b32_dpp v224, v38 quad_perm:[1,0,3,2] row_mask:0xf bank_mask:0xf
	v_mov_b32_dpp v225, v34 quad_perm:[1,0,3,2] row_mask:0xf bank_mask:0xf
	v_cndmask_b32_e32 v226, v38, v225, vcc
	v_cndmask_b32_e32 v227, v224, v34, vcc
	v_cvt_pk_bf16_f32 v0, v226, v227
	global_store_dword v[66:67], v0, off offset:320
	v_lshl_add_u64 v[66:67], v[66:67], 0, s[0:1]
	v_mov_b32_dpp v224, v63 quad_perm:[1,0,3,2] row_mask:0xf bank_mask:0xf
	v_mov_b32_dpp v225, v59 quad_perm:[1,0,3,2] row_mask:0xf bank_mask:0xf
	v_cndmask_b32_e32 v226, v63, v225, vcc
	v_cndmask_b32_e32 v227, v224, v59, vcc
	v_cvt_pk_bf16_f32 v0, v226, v227
	global_store_dword v[66:67], v0, off
	v_mov_b32_dpp v224, v55 quad_perm:[1,0,3,2] row_mask:0xf bank_mask:0xf
	v_mov_b32_dpp v225, v51 quad_perm:[1,0,3,2] row_mask:0xf bank_mask:0xf
	v_cndmask_b32_e32 v226, v55, v225, vcc
	v_cndmask_b32_e32 v227, v224, v51, vcc
	v_cvt_pk_bf16_f32 v0, v226, v227
	global_store_dword v[66:67], v0, off offset:64
	v_mov_b32_dpp v224, v47 quad_perm:[1,0,3,2] row_mask:0xf bank_mask:0xf
	v_mov_b32_dpp v225, v43 quad_perm:[1,0,3,2] row_mask:0xf bank_mask:0xf
	v_cndmask_b32_e32 v226, v47, v225, vcc
	v_cndmask_b32_e32 v227, v224, v43, vcc
	v_cvt_pk_bf16_f32 v0, v226, v227
	global_store_dword v[66:67], v0, off offset:256
	v_mov_b32_dpp v224, v39 quad_perm:[1,0,3,2] row_mask:0xf bank_mask:0xf
	v_mov_b32_dpp v225, v35 quad_perm:[1,0,3,2] row_mask:0xf bank_mask:0xf
	v_cndmask_b32_e32 v226, v39, v225, vcc
	v_cndmask_b32_e32 v227, v224, v35, vcc
	v_cvt_pk_bf16_f32 v0, v226, v227
	v_lshl_add_u64 v[34:35], v[66:67], 0, s[0:1]
	global_store_dword v[66:67], v0, off offset:320
	v_mov_b32_dpp v224, v64 quad_perm:[1,0,3,2] row_mask:0xf bank_mask:0xf
	v_mov_b32_dpp v225, v60 quad_perm:[1,0,3,2] row_mask:0xf bank_mask:0xf
	v_cndmask_b32_e32 v226, v64, v225, vcc
	v_cndmask_b32_e32 v227, v224, v60, vcc
	v_cvt_pk_bf16_f32 v0, v226, v227
	global_store_dword v[34:35], v0, off
	v_mov_b32_dpp v224, v56 quad_perm:[1,0,3,2] row_mask:0xf bank_mask:0xf
	v_mov_b32_dpp v225, v52 quad_perm:[1,0,3,2] row_mask:0xf bank_mask:0xf
	v_cndmask_b32_e32 v226, v56, v225, vcc
	v_cndmask_b32_e32 v227, v224, v52, vcc
	v_cvt_pk_bf16_f32 v0, v226, v227
	global_store_dword v[34:35], v0, off offset:64
	v_mov_b32_dpp v224, v48 quad_perm:[1,0,3,2] row_mask:0xf bank_mask:0xf
	v_mov_b32_dpp v225, v44 quad_perm:[1,0,3,2] row_mask:0xf bank_mask:0xf
	v_cndmask_b32_e32 v226, v48, v225, vcc
	v_cndmask_b32_e32 v227, v224, v44, vcc
	v_cvt_pk_bf16_f32 v0, v226, v227
	global_store_dword v[34:35], v0, off offset:256
	v_mov_b32_dpp v224, v40 quad_perm:[1,0,3,2] row_mask:0xf bank_mask:0xf
	v_mov_b32_dpp v225, v36 quad_perm:[1,0,3,2] row_mask:0xf bank_mask:0xf
	v_cndmask_b32_e32 v226, v40, v225, vcc
	v_cndmask_b32_e32 v227, v224, v36, vcc
	v_cvt_pk_bf16_f32 v0, v226, v227
	global_store_dword v[34:35], v0, off offset:320
	v_lshl_add_u64 v[34:35], v[34:35], 0, s[0:1]
	v_mov_b32_dpp v224, v65 quad_perm:[1,0,3,2] row_mask:0xf bank_mask:0xf
	v_mov_b32_dpp v225, v61 quad_perm:[1,0,3,2] row_mask:0xf bank_mask:0xf
	v_cndmask_b32_e32 v226, v65, v225, vcc
	v_cndmask_b32_e32 v227, v224, v61, vcc
	v_cvt_pk_bf16_f32 v0, v226, v227
	global_store_dword v[34:35], v0, off
	v_mov_b32_dpp v224, v57 quad_perm:[1,0,3,2] row_mask:0xf bank_mask:0xf
	v_mov_b32_dpp v225, v53 quad_perm:[1,0,3,2] row_mask:0xf bank_mask:0xf
	v_cndmask_b32_e32 v226, v57, v225, vcc
	v_cndmask_b32_e32 v227, v224, v53, vcc
	v_cvt_pk_bf16_f32 v0, v226, v227
	global_store_dword v[34:35], v0, off offset:64
	v_mov_b32_dpp v224, v49 quad_perm:[1,0,3,2] row_mask:0xf bank_mask:0xf
	v_mov_b32_dpp v225, v45 quad_perm:[1,0,3,2] row_mask:0xf bank_mask:0xf
	v_cndmask_b32_e32 v226, v49, v225, vcc
	v_cndmask_b32_e32 v227, v224, v45, vcc
	v_cvt_pk_bf16_f32 v0, v226, v227
	global_store_dword v[34:35], v0, off offset:256
	v_mov_b32_dpp v224, v41 quad_perm:[1,0,3,2] row_mask:0xf bank_mask:0xf
	v_mov_b32_dpp v225, v37 quad_perm:[1,0,3,2] row_mask:0xf bank_mask:0xf
	v_cndmask_b32_e32 v226, v41, v225, vcc
	v_cndmask_b32_e32 v227, v224, v37, vcc
	v_cvt_pk_bf16_f32 v0, v226, v227
	global_store_dword v[34:35], v0, off offset:320
	v_lshl_add_u64 v[34:35], v[34:35], 0, s[0:1]
	v_mov_b32_dpp v224, v30 quad_perm:[1,0,3,2] row_mask:0xf bank_mask:0xf
	v_mov_b32_dpp v225, v26 quad_perm:[1,0,3,2] row_mask:0xf bank_mask:0xf
	v_cndmask_b32_e32 v226, v30, v225, vcc
	v_cndmask_b32_e32 v227, v224, v26, vcc
	v_cvt_pk_bf16_f32 v0, v226, v227
	global_store_dword v[34:35], v0, off
	v_mov_b32_dpp v224, v22 quad_perm:[1,0,3,2] row_mask:0xf bank_mask:0xf
; __device__ __forceinline__ unsigned cvt_pk_bf16(float lo, float hi) { unsigned r; asm volatile("v_cvt_pk_bf16_f32 %0, %1, %2" : "=v"(r) : "v"(lo), "v"(hi)); return r; }
;     __device__ __forceinline__ void operator()(f32x4 (&acc)[2][2][4][2], const Unit& u, int wr, int wc, int fr, int fq) const {
;     ...
;             bf16_t* tp = T + (size_t)(colt - t_col0) * ldt + row0;
; #pragma unroll
;             for (int bj = 0; bj < 2; ++bj) {
; #pragma unroll
;                 for (int n = 0; n < 2; ++n)
; #pragma unroll
;                     for (int j = 0; j < 4; ++j) {
; #pragma unroll
;                         for (int ai = 0; ai < 2; ++ai)
; #pragma unroll
;                             for (int m = 0; m < 4; ++m) tp[ai * HALF + m * 16] = (bf16_t)(cvt_pk_bf16(acc[ai][bj][m][n][j], 0.f) & 0xffffu);
;                         tp += ldt; asm volatile("" : "+v"(tp)); }
;                 tp += (size_t)120 * ldt; asm volatile("" : "+v"(tp)); }
	v_mov_b32_dpp v225, v18 quad_perm:[1,0,3,2] row_mask:0xf bank_mask:0xf
	v_cndmask_b32_e32 v226, v22, v225, vcc
	v_cndmask_b32_e32 v227, v224, v18, vcc
	v_cvt_pk_bf16_f32 v0, v226, v227
	global_store_dword v[34:35], v0, off offset:64
	v_mov_b32_dpp v224, v14 quad_perm:[1,0,3,2] row_mask:0xf bank_mask:0xf
	v_mov_b32_dpp v225, v10 quad_perm:[1,0,3,2] row_mask:0xf bank_mask:0xf
	v_cndmask_b32_e32 v226, v14, v225, vcc
	v_cndmask_b32_e32 v227, v224, v10, vcc
	v_cvt_pk_bf16_f32 v0, v226, v227
	global_store_dword v[34:35], v0, off offset:256
	v_mov_b32_dpp v224, v6 quad_perm:[1,0,3,2] row_mask:0xf bank_mask:0xf
	v_mov_b32_dpp v225, v2 quad_perm:[1,0,3,2] row_mask:0xf bank_mask:0xf
	v_cndmask_b32_e32 v226, v6, v225, vcc
	v_cndmask_b32_e32 v227, v224, v2, vcc
	v_cvt_pk_bf16_f32 v0, v226, v227
	global_store_dword v[34:35], v0, off offset:320
	v_lshl_add_u64 v[34:35], v[34:35], 0, s[0:1]
	v_mov_b32_dpp v224, v31 quad_perm:[1,0,3,2] row_mask:0xf bank_mask:0xf
	v_mov_b32_dpp v225, v27 quad_perm:[1,0,3,2] row_mask:0xf bank_mask:0xf
	v_cndmask_b32_e32 v226, v31, v225, vcc
	v_cndmask_b32_e32 v227, v224, v27, vcc
	v_cvt_pk_bf16_f32 v0, v226, v227
	global_store_dword v[34:35], v0, off
	v_mov_b32_dpp v224, v23 quad_perm:[1,0,3,2] row_mask:0xf bank_mask:0xf
	v_mov_b32_dpp v225, v19 quad_perm:[1,0,3,2] row_mask:0xf bank_mask:0xf
	v_cndmask_b32_e32 v226, v23, v225, vcc
	v_cndmask_b32_e32 v227, v224, v19, vcc
	v_cvt_pk_bf16_f32 v0, v226, v227
	global_store_dword v[34:35], v0, off offset:64
	v_mov_b32_dpp v224, v15 quad_perm:[1,0,3,2] row_mask:0xf bank_mask:0xf
	v_mov_b32_dpp v225, v11 quad_perm:[1,0,3,2] row_mask:0xf bank_mask:0xf
	v_cndmask_b32_e32 v226, v15, v225, vcc
	v_cndmask_b32_e32 v227, v224, v11, vcc
	v_cvt_pk_bf16_f32 v0, v226, v227
	global_store_dword v[34:35], v0, off offset:256
	v_mov_b32_dpp v224, v7 quad_perm:[1,0,3,2] row_mask:0xf bank_mask:0xf
	v_mov_b32_dpp v225, v3 quad_perm:[1,0,3,2] row_mask:0xf bank_mask:0xf
	v_cndmask_b32_e32 v226, v7, v225, vcc
	v_cndmask_b32_e32 v227, v224, v3, vcc
	v_cvt_pk_bf16_f32 v0, v226, v227
	v_lshl_add_u64 v[2:3], v[34:35], 0, s[0:1]
	global_store_dword v[34:35], v0, off offset:320
	v_mov_b32_dpp v224, v32 quad_perm:[1,0,3,2] row_mask:0xf bank_mask:0xf
	v_mov_b32_dpp v225, v28 quad_perm:[1,0,3,2] row_mask:0xf bank_mask:0xf
	v_cndmask_b32_e32 v226, v32, v225, vcc
	v_cndmask_b32_e32 v227, v224, v28, vcc
	v_cvt_pk_bf16_f32 v0, v226, v227
	global_store_dword v[2:3], v0, off
	v_mov_b32_dpp v224, v24 quad_perm:[1,0,3,2] row_mask:0xf bank_mask:0xf
	v_mov_b32_dpp v225, v20 quad_perm:[1,0,3,2] row_mask:0xf bank_mask:0xf
	v_cndmask_b32_e32 v226, v24, v225, vcc
	v_cndmask_b32_e32 v227, v224, v20, vcc
	v_cvt_pk_bf16_f32 v0, v226, v227
	global_store_dword v[2:3], v0, off offset:64
	v_mov_b32_dpp v224, v16 quad_perm:[1,0,3,2] row_mask:0xf bank_mask:0xf
	v_mov_b32_dpp v225, v12 quad_perm:[1,0,3,2] row_mask:0xf bank_mask:0xf
	v_cndmask_b32_e32 v226, v16, v225, vcc
	v_cndmask_b32_e32 v227, v224, v12, vcc
	v_cvt_pk_bf16_f32 v0, v226, v227
	global_store_dword v[2:3], v0, off offset:256
	v_mov_b32_dpp v224, v8 quad_perm:[1,0,3,2] row_mask:0xf bank_mask:0xf
	v_mov_b32_dpp v225, v4 quad_perm:[1,0,3,2] row_mask:0xf bank_mask:0xf
	v_cndmask_b32_e32 v226, v8, v225, vcc
	v_cndmask_b32_e32 v227, v224, v4, vcc
	v_cvt_pk_bf16_f32 v0, v226, v227
	global_store_dword v[2:3], v0, off offset:320
	v_lshl_add_u64 v[2:3], v[2:3], 0, s[0:1]
	v_mov_b32_dpp v224, v33 quad_perm:[1,0,3,2] row_mask:0xf bank_mask:0xf
	v_mov_b32_dpp v225, v29 quad_perm:[1,0,3,2] row_mask:0xf bank_mask:0xf
	v_cndmask_b32_e32 v226, v33, v225, vcc
	v_cndmask_b32_e32 v227, v224, v29, vcc
	v_cvt_pk_bf16_f32 v0, v226, v227
	global_store_dword v[2:3], v0, off
	v_mov_b32_dpp v224, v25 quad_perm:[1,0,3,2] row_mask:0xf bank_mask:0xf
	v_mov_b32_dpp v225, v21 quad_perm:[1,0,3,2] row_mask:0xf bank_mask:0xf
	v_cndmask_b32_e32 v226, v25, v225, vcc
	v_cndmask_b32_e32 v227, v224, v21, vcc
	v_cvt_pk_bf16_f32 v0, v226, v227
	global_store_dword v[2:3], v0, off offset:64
	v_mov_b32_dpp v224, v17 quad_perm:[1,0,3,2] row_mask:0xf bank_mask:0xf
	v_mov_b32_dpp v225, v13 quad_perm:[1,0,3,2] row_mask:0xf bank_mask:0xf
	v_cndmask_b32_e32 v226, v17, v225, vcc
	v_cndmask_b32_e32 v227, v224, v13, vcc
	v_cvt_pk_bf16_f32 v0, v226, v227
	global_store_dword v[2:3], v0, off offset:256
	v_mov_b32_dpp v224, v9 quad_perm:[1,0,3,2] row_mask:0xf bank_mask:0xf
	v_mov_b32_dpp v225, v5 quad_perm:[1,0,3,2] row_mask:0xf bank_mask:0xf
	v_cndmask_b32_e32 v226, v9, v225, vcc
	v_cndmask_b32_e32 v227, v224, v5, vcc
	v_cvt_pk_bf16_f32 v0, v226, v227
	global_store_dword v[2:3], v0, off offset:320
	v_lshl_add_u64 v[2:3], v[2:3], 0, s[0:1]
	s_nop 0
	v_lshl_add_u64 v[2:3], v[2:3], 0, s[6:7]
	s_andn2_b64 vcc, exec, s[4:5]
	s_mov_b64 s[0:1], -1
	s_cbranch_vccnz .LBB0_261
